# baseline (speedup 1.0000x reference)
.LBB0_110:
	s_or_saveexec_b64 s[88:89], s[28:29]
	v_mov_b32_e32 v224, 2
	s_xor_b64 exec, exec, s[88:89]
	s_cbranch_execz .LBB0_212
	v_cmp_lt_i32_e32 vcc, 3, v223
	s_mov_b64 s[90:91], s[46:47]
	s_and_saveexec_b64 s[8:9], vcc
	s_xor_b64 s[28:29], exec, s[8:9]
	s_or_b64 s[90:91], s[46:47], exec
	s_andn2_saveexec_b64 s[92:93], s[28:29]
	s_cbranch_execz .LBB0_211
	v_mov_b32_e32 v2, v190
	v_cndmask_b32_e64 v3, 0, 64, s[4:5]
	v_and_b32_e32 v0, 63, v2
	v_or_b32_e32 v3, v0, v3
	v_readlane_b32 s36, v255, 44
	v_readlane_b32 s28, v255, 36
	v_lshlrev_b32_e32 v3, 2, v3
	v_readlane_b32 s40, v255, 48
	v_readlane_b32 s41, v255, 49
	v_readlane_b32 s29, v255, 37
	v_readlane_b32 s42, v255, 50
	v_readlane_b32 s43, v255, 51
	s_nop 1
	global_load_dword v4, v3, s[40:41]
	s_nop 1
	global_load_dword v5, v3, s[42:43]
	v_readlane_b32 s30, v255, 38
	v_readlane_b32 s31, v255, 39
	global_load_dword v6, v3, s[28:29]
	s_nop 3
	global_load_dword v3, v3, s[30:31]
	v_lshlrev_b32_e32 v0, 2, v0
	v_xor_b32_e32 v7, 0x80, v0
	v_readlane_b32 s8, v255, 7
	v_readlane_b32 s37, v255, 45
	v_readlane_b32 s38, v255, 46
	v_readlane_b32 s39, v255, 47
	v_readlane_b32 s9, v255, 8
	s_mov_b32 s39, 0x160000
	s_mov_b32 s38, 0x120000
	s_mov_b32 s37, 0x60000
	s_mov_b32 s36, 0x140000
	s_andn2_b64 vcc, exec, s[8:9]
	s_waitcnt vmcnt(2)
	v_mul_f32_e32 v8, v4, v5
	ds_bpermute_b32 v8, v7, v8
	s_waitcnt vmcnt(0)
	v_mul_f32_e32 v9, v6, v3
	ds_bpermute_b32 v7, v7, v9
	v_xor_b32_e32 v9, 64, v0
	s_waitcnt lgkmcnt(1)
	v_fmac_f32_e32 v8, v4, v5
	v_xor_b32_e32 v5, 32, v0
	s_waitcnt lgkmcnt(0)
	v_fmac_f32_e32 v7, v6, v3
	ds_bpermute_b32 v3, v9, v8
	ds_bpermute_b32 v4, v9, v7
	s_waitcnt lgkmcnt(1)
	v_add_f32_e32 v3, v8, v3
	s_waitcnt lgkmcnt(0)
	v_add_f32_e32 v4, v7, v4
	ds_bpermute_b32 v6, v5, v3
	ds_bpermute_b32 v5, v5, v4
	v_xor_b32_e32 v7, 16, v0
	s_waitcnt lgkmcnt(1)
	v_add_f32_e32 v3, v3, v6
	s_waitcnt lgkmcnt(0)
	v_add_f32_e32 v4, v4, v5
	ds_bpermute_b32 v5, v7, v3
	ds_bpermute_b32 v6, v7, v4
	v_xor_b32_e32 v7, 8, v0
	s_waitcnt lgkmcnt(1)
	v_add_f32_e32 v3, v3, v5
	s_waitcnt lgkmcnt(0)
	v_add_f32_e32 v5, v4, v6
	ds_bpermute_b32 v4, v7, v3
	ds_bpermute_b32 v6, v7, v5
	v_xor_b32_e32 v7, 4, v0
	s_waitcnt lgkmcnt(1)
	v_add_f32_e32 v4, v3, v4
	s_waitcnt lgkmcnt(0)
	v_add_f32_e32 v0, v5, v6
	ds_bpermute_b32 v5, v7, v4
	ds_bpermute_b32 v3, v7, v0
	s_cbranch_vccnz .LBB0_211
	s_waitcnt lgkmcnt(1)
	v_add_f32_e32 v4, v4, v5
	v_mul_f32_e32 v5, 0x3fb8aa3b, v4
	s_mov_b32 s2, 0x3fb8aa3b
	v_fma_f32 v6, v4, s2, -v5
	v_rndne_f32_e32 v7, v5
	v_fmac_f32_e32 v6, 0x32a5705f, v4
	v_sub_f32_e32 v5, v5, v7
	v_add_f32_e32 v5, v5, v6
	v_exp_f32_e32 v5, v5
	v_cvt_i32_f32_e32 v6, v7
	s_waitcnt lgkmcnt(0)
	v_add_f32_e32 v0, v0, v3
	v_mov_b32_e32 v3, 0x3e4ccccd
	v_mov_b32_e32 v7, 0x3eb60549
	v_ldexp_f32 v5, v5, v6
	v_mul_f32_e32 v6, 0x3fb8aa3b, v0
	v_cndmask_b32_e64 v3, v3, v7, s[4:5]
	v_fma_f32 v7, v0, s2, -v6
	v_rndne_f32_e32 v8, v6
	v_fmac_f32_e32 v7, 0x32a5705f, v0
	v_sub_f32_e32 v6, v6, v8
	v_add_f32_e32 v6, v6, v7
	v_exp_f32_e32 v6, v6
	v_cvt_i32_f32_e32 v7, v8
	s_mov_b32 s2, 0xc2ce8ed0
	v_cmp_ngt_f32_e32 vcc, s2, v4
	s_mov_b32 s8, 0x42b17218
	v_cndmask_b32_e64 v142, 0, v208, s[4:5]
	v_cndmask_b32_e32 v5, 0, v5, vcc
	v_cmp_nlt_f32_e32 vcc, s8, v4
	v_mov_b32_e32 v143, v1
	v_sub_f32_e32 v161, 1.0, v3
	v_cndmask_b32_e32 v4, v206, v5, vcc
	v_ldexp_f32 v5, v6, v7
	v_cmp_ngt_f32_e32 vcc, s2, v0
	v_readlane_b32 s95, v255, 0
	s_mov_b32 s50, 0x3fb8aa3b
	v_cndmask_b32_e32 v5, 0, v5, vcc
	v_cmp_nlt_f32_e32 vcc, s8, v0
	v_readlane_b32 s8, v255, 1
	v_readlane_b32 s9, v255, 2
	s_load_dwordx2 s[8:9], s[8:9], 0x98
	v_cndmask_b32_e32 v0, v206, v5, vcc
	v_sub_f32_e32 v0, v4, v0
	v_add_f32_e32 v153, v3, v0
	v_cndmask_b32_e64 v0, 0, v207, s[4:5]
	s_waitcnt lgkmcnt(0)
	v_lshl_add_u64 v[140:141], s[8:9], 0, v[0:1]
	v_ashrrev_i32_e32 v0, 2, v2
	v_lshl_add_u64 v[2:3], s[22:23], 0, v[142:143]
	s_mov_b64 s[8:9], 0x2f550000
	v_and_b32_e32 v174, -16, v0
	v_cndmask_b32_e64 v0, 0, v209, s[4:5]
	v_lshl_add_u64 v[144:145], v[2:3], 0, s[8:9]
	s_mov_b64 s[8:9], 0x30e50000
	v_lshl_add_u64 v[146:147], v[2:3], 0, s[8:9]
	v_lshl_add_u64 v[2:3], s[22:23], 0, v[0:1]
	s_mov_b64 s[8:9], 0x2f050000
	v_lshl_add_u64 v[148:149], v[2:3], 0, s[8:9]
	s_mov_b64 s[8:9], 0x30950000
	v_cndmask_b32_e64 v175, 0, 8, s[4:5]
	v_lshl_add_u64 v[150:151], v[2:3], 0, s[8:9]
	v_sub_u32_e32 v176, 0, v174
	v_add_u32_e32 v177, 0x2cd, v174
	v_readfirstlane_b32 s8, v190
	s_nop 3
	s_lshr_b32 s8, s8, 8
	s_cmp_eq_u32 s8, 1
	s_cbranch_scc0 .Lattn_prio_done
	s_setprio 1
.Lattn_prio_done:
	s_mov_b32 s19, s95
	v_readlane_b32 s94, v255, 33
	s_branch .LBB0_136

.LBB0_211:
	s_setprio 0
	s_or_b64 exec, exec, s[92:93]
	s_andn2_b64 s[8:9], s[46:47], exec
	s_and_b64 s[28:29], s[90:91], exec
	v_mov_b32_e32 v224, 1
	s_or_b64 s[46:47], s[8:9], s[28:29]
